# attention phase: blocks lb>=32 run the dense items before the band items (co-resident blocks in different work)
# baseline (speedup 1.0000x reference)
; DI void run_phase(const Params& p, int ph, char* smem, bool never) {
;   const int G = gridDim.x, B = blockIdx.x;
;   if (ph == 0) {
;     for (int i = B; i < 6097; i += G) prep_item(p, i, (float*)smem);
;     for (int i = B; i < 1024; i += G) norm_rows_bf16(p.x, p.norm_g, P_XN, i);
;   } else if (ph == 14) {
;     for (int i = B; i < 1024; i += G) norm_rows_f32(p.out, p.final_g, i);
;   } else if (ph == 7) {
;     for (int i = B; i < 1024; i += G) norm_rows_bf16(p.out, p.norm_g + 1024, P_XN, i);
;   } else {
;     const int l = ph > 7 ? 1 : 0; const int s = ph > 7 ? ph - 8 : ph - 1;
;     const int xcd = B & 7, lb = B >> 3, nl = G >> 3;
;     if (s == 0) {
; __global__ void __launch_bounds__(256, 2) mega(Params p, int ph_lo, int ph_hi) {
;     ...
;   for (int ph = ph_lo; ph < ph_hi; ++ph) {
;     run_phase(p, ph, smem, ph_hi == 12345);
.LBB0_17:
	v_writelane_b32 v253, s18, 2
	s_cmp_ge_i32 s18, s19
	s_nop 0
	v_writelane_b32 v253, s19, 3
	s_cbranch_scc1 .LBB0_387
	s_load_dwordx16 s[60:75], s[0:1], 0x0
	s_cmpk_lt_i32 s2, 0x400
	s_mov_b32 s10, s2
	s_cselect_b64 s[2:3], -1, 0
	v_writelane_b32 v253, s2, 4
	s_waitcnt lgkmcnt(0)
	s_add_u32 s30, s62, 0x1000
	s_addc_u32 s31, s63, 0
	v_writelane_b32 v253, s3, 5
	s_add_u32 s0, s58, 0x2ca4000
	v_writelane_b32 v253, s0, 6
	s_addc_u32 s0, s59, 0
	s_cmpk_lt_i32 s10, 0x17d1
	v_writelane_b32 v253, s0, 7
	s_cselect_b64 s[2:3], -1, 0
	v_writelane_b32 v253, s2, 8
	s_mov_b32 s95, 0
	s_mul_i32 s1, s21, s20
	v_writelane_b32 v253, s3, 9
	s_add_u32 s2, s58, 0x2ca0000
	s_addc_u32 s3, s59, 0
	v_writelane_b32 v253, s2, 10
	s_mov_b32 s21, s95
	s_mul_i32 s1, s1, s12
	v_writelane_b32 v253, s3, 11
	s_add_u32 s2, s58, 0x2ca2000
	s_addc_u32 s3, s59, 0
	s_add_u32 s88, s58, 0x2ba0000
	v_writelane_b32 v253, s2, 12
	s_addc_u32 s89, s59, 0
	s_add_u32 s0, s58, 0x2b60000
	v_writelane_b32 v253, s3, 13
	v_writelane_b32 v253, s0, 14
	s_addc_u32 s0, s59, 0
	v_writelane_b32 v253, s0, 15
	s_add_u32 s0, s58, 0x2b00000
	v_writelane_b32 v253, s0, 16
	s_addc_u32 s0, s59, 0
	v_writelane_b32 v253, s0, 17
	s_add_u32 s0, s58, 0x2700000
	v_writelane_b32 v253, s0, 18
	s_addc_u32 s0, s59, 0
	v_writelane_b32 v253, s0, 19
	s_add_u32 s0, s58, 0x2300000
	v_writelane_b32 v253, s0, 20
	s_addc_u32 s0, s59, 0
	v_writelane_b32 v253, s0, 21
	s_add_u32 s0, s58, 0x1300000
	v_writelane_b32 v253, s0, 22
	s_addc_u32 s0, s59, 0
	s_and_b32 s2, s10, 7
	s_ashr_i32 s9, s10, 3
	s_ashr_i32 s14, s20, 3
	s_cmpk_lt_i32 s9, 0x200
	v_writelane_b32 v253, s0, 23
	s_cselect_b64 s[4:5], -1, 0
	v_writelane_b32 v253, s4, 24
	s_cmpk_lt_u32 s10, 0x1000
	v_mov_b32_e32 v1, 0
	v_writelane_b32 v253, s5, 25
	s_cselect_b64 s[4:5], -1, 0
	v_writelane_b32 v253, s4, 26
	s_lshl_b32 s0, s10, 8
	v_mbcnt_lo_u32_b32 v0, -1, 0
	v_writelane_b32 v253, s5, 27
	v_writelane_b32 v253, s0, 28
	s_lshl_b64 s[4:5], s[20:21], 8
	v_writelane_b32 v253, s4, 29
	v_mbcnt_hi_u32_b32 v204, -1, v0
	v_and_b32_e32 v0, 64, v204
	v_writelane_b32 v253, s5, 30
	s_add_u32 s4, s58, 0x1dca4000
	s_addc_u32 s5, s59, 0
	s_add_u32 s18, s58, 0x6ca4000
	s_addc_u32 s19, s59, 0
	v_writelane_b32 v253, s4, 31
	s_cmpk_lt_i32 s10, 0x1000
	v_mov_b32_e32 v190, 0x358637bd
	v_writelane_b32 v253, s5, 32
	s_cselect_b64 s[4:5], -1, 0
	v_writelane_b32 v253, s4, 33
	s_cmpk_lt_i32 s9, 0x100
	v_add_u32_e32 v189, 64, v0
	v_writelane_b32 v253, s5, 34
	s_cselect_b64 s[4:5], -1, 0
	v_writelane_b32 v253, s4, 35
	v_xor_b32_e32 v252, 32, v204
	v_xor_b32_e32 v191, 16, v204
	v_writelane_b32 v253, s5, 36
	s_and_b32 s4, s10, 3
	s_lshl_b32 s0, s4, 6
	s_lshl_b32 s3, s4, 7
	s_add_u32 s5, s18, s3
	v_writelane_b32 v253, s5, 37
	s_addc_u32 s5, s19, 0
	s_add_u32 s6, s58, 0x19ca4000
	s_addc_u32 s7, s59, 0
	s_mul_i32 s8, s4, 0xc0
	v_writelane_b32 v253, s5, 38
	s_add_u32 s4, s6, s8
	v_writelane_b32 v253, s4, 39
	v_writelane_b32 v253, s6, 40
	s_addc_u32 s4, s7, 0
	v_xor_b32_e32 v192, 8, v204
	v_writelane_b32 v253, s7, 41
	v_writelane_b32 v253, s4, 42
	s_add_u32 s4, s58, s8
	s_addc_u32 s5, s59, 0
	s_add_u32 s4, s4, 0x1b4a4000
	v_writelane_b32 v253, s4, 43
	s_addc_u32 s4, s5, 0
	v_writelane_b32 v253, s4, 44
	s_add_u32 s4, s58, s3
	s_addc_u32 s5, s59, 0
	v_writelane_b32 v253, s3, 45
	s_add_u32 s3, s4, 0x1cca4000
	v_writelane_b32 v253, s3, 46
	s_addc_u32 s3, s5, 0
	s_cmpk_lt_i32 s10, 0x800
	v_writelane_b32 v253, s3, 47
	s_cselect_b64 s[4:5], -1, 0
	v_writelane_b32 v253, s4, 48
	s_cmpk_lt_i32 s9, 0x260
	v_xor_b32_e32 v193, 4, v204
	v_writelane_b32 v253, s5, 49
	s_cselect_b64 s[4:5], -1, 0
	v_writelane_b32 v253, s4, 50
	s_cmpk_lt_i32 s9, 0x80
	v_xor_b32_e32 v194, 2, v204
	v_writelane_b32 v253, s5, 51
	s_cselect_b64 s[4:5], -1, 0
	v_writelane_b32 v253, s4, 52
	v_xor_b32_e32 v195, 1, v204
	v_mov_b32_e32 v205, 0x100
	v_writelane_b32 v253, s5, 53
	v_writelane_b32 v253, s2, 54
	s_lshl_b32 s2, s2, 3
	v_writelane_b32 v253, s2, 55
	s_add_u32 s2, s58, 0x1de24200
	s_addc_u32 s3, s59, 0
	v_writelane_b32 v253, s2, 56
	v_mov_b32_e32 v202, 0xf149f2ca
	v_mov_b32_e32 v203, 0x80
	v_writelane_b32 v253, s3, 57
	s_add_u32 s2, s58, 0x1de24400
	s_addc_u32 s3, s59, 0
	v_writelane_b32 v253, s2, 58
	s_movk_i32 s85, 0x1000
	s_movk_i32 s93, 0x80
	v_writelane_b32 v253, s3, 59
	s_add_u32 s2, s58, 0x1de24500
	s_addc_u32 s3, s59, 0
	v_writelane_b32 v253, s2, 60
	s_mov_b32 s77, 0x20000
	s_mov_b32 s76, 0x2ca4000
	v_writelane_b32 v253, s3, 61
	s_add_u32 s2, s58, 0x1de24600
	s_addc_u32 s3, s59, 0
	v_writelane_b32 v253, s2, 62
	s_mov_b32 s15, 0x2cc4000
	s_mov_b32 s80, 0xc000
	v_writelane_b32 v253, s3, 63
	s_add_u32 s2, s58, 0x1de24700
	s_addc_u32 s3, s59, 0
	v_writelane_b32 v254, s2, 0
	s_mov_b32 s33, 0xaaaaaaab
	s_mov_b32 s92, 0x40000
	v_writelane_b32 v254, s3, 1
	s_add_u32 s2, s58, 0x1de24800
	s_addc_u32 s3, s59, 0
	v_writelane_b32 v254, s2, 2
	s_mov_b32 s81, 0x60000
	s_mov_b32 s40, 0x3f317217
	v_writelane_b32 v254, s3, 3
	s_add_u32 s2, s58, 0x1de24900
	s_addc_u32 s3, s59, 0
	v_writelane_b32 v254, s2, 4
	s_mov_b32 s41, 0x7f800000
	s_mov_b64 s[86:87], 0x4000
	v_writelane_b32 v254, s3, 5
	s_add_u32 s2, s58, 0x1de24a00
	s_addc_u32 s3, s59, 0
	v_writelane_b32 v254, s2, 6
	s_mov_b64 s[90:91], 0x4800
	s_nop 0
	v_writelane_b32 v254, s3, 7
	s_add_u32 s2, s58, 0x1de24b00
	s_addc_u32 s3, s59, 0
	v_writelane_b32 v254, s2, 8
	s_nop 1
	v_writelane_b32 v254, s3, 9
	s_add_u32 s2, s58, 0x1de24c00
	s_addc_u32 s3, s59, 0
	v_writelane_b32 v254, s2, 10
	s_nop 1
	v_writelane_b32 v254, s3, 11
	s_add_u32 s2, s58, 0x1de24d00
	s_addc_u32 s3, s59, 0
	v_writelane_b32 v254, s2, 12
	s_nop 1
	v_writelane_b32 v254, s3, 13
	s_add_u32 s2, s58, 0x1de24e00
; DI void run_phase(const Params& p, int ph, char* smem, bool never) {
;   const int G = gridDim.x, B = blockIdx.x;
;   if (ph == 0) {
;     for (int i = B; i < 6097; i += G) prep_item(p, i, (float*)smem);
;     for (int i = B; i < 1024; i += G) norm_rows_bf16(p.x, p.norm_g, P_XN, i);
;   } else if (ph == 14) {
;     for (int i = B; i < 1024; i += G) norm_rows_f32(p.out, p.final_g, i);
;   } else if (ph == 7) {
;     for (int i = B; i < 1024; i += G) norm_rows_bf16(p.out, p.norm_g + 1024, P_XN, i);
;   } else {
;     const int l = ph > 7 ? 1 : 0; const int s = ph > 7 ? ph - 8 : ph - 1;
;     const int xcd = B & 7, lb = B >> 3, nl = G >> 3;
;     if (s == 0) {
; __global__ void __launch_bounds__(256, 2) mega(Params p, int ph_lo, int ph_hi) {
;     ...
;   for (int ph = ph_lo; ph < ph_hi; ++ph) {
;     run_phase(p, ph, smem, ph_hi == 12345);
	s_addc_u32 s3, s59, 0
	v_writelane_b32 v254, s2, 14
	s_nop 1
	v_writelane_b32 v254, s3, 15
	s_add_u32 s2, s58, 0x1de24f00
	s_addc_u32 s3, s59, 0
	v_writelane_b32 v254, s2, 16
	s_nop 1
	v_writelane_b32 v254, s3, 17
	s_add_u32 s2, s58, 0x1de25000
	s_addc_u32 s3, s59, 0
	v_writelane_b32 v254, s2, 18
	s_nop 1
	v_writelane_b32 v254, s3, 19
	s_add_u32 s2, s58, 0x1de25100
	s_addc_u32 s3, s59, 0
	v_writelane_b32 v254, s2, 20
	s_nop 1
	v_writelane_b32 v254, s3, 21
	s_add_u32 s2, s58, 0x1de25200
	s_addc_u32 s3, s59, 0
	v_writelane_b32 v254, s2, 22
	s_nop 1
	v_writelane_b32 v254, s3, 23
	s_add_u32 s2, s58, 0x1de25300
	s_addc_u32 s3, s59, 0
	v_writelane_b32 v254, s2, 24
	s_cmp_eq_u32 s13, 15
	s_nop 0
	v_writelane_b32 v254, s3, 25
	s_cselect_b64 s[2:3], -1, 0
	v_writelane_b32 v254, s2, 26
	s_cmp_eq_u32 s13, 14
	s_nop 0
	v_writelane_b32 v254, s3, 27
	s_cselect_b64 s[2:3], -1, 0
	v_writelane_b32 v254, s2, 28
	s_cmp_eq_u32 s13, 13
	s_nop 0
	v_writelane_b32 v254, s3, 29
	s_cselect_b64 s[2:3], -1, 0
	v_writelane_b32 v254, s2, 30
	s_cmp_eq_u32 s13, 12
	s_nop 0
	v_writelane_b32 v254, s3, 31
	s_cselect_b64 s[2:3], -1, 0
	v_writelane_b32 v254, s2, 32
	s_cmp_eq_u32 s13, 11
	s_nop 0
	v_writelane_b32 v254, s3, 33
	s_cselect_b64 s[2:3], -1, 0
	v_writelane_b32 v254, s2, 34
	s_cmp_eq_u32 s13, 10
	s_nop 0
	v_writelane_b32 v254, s3, 35
	s_cselect_b64 s[2:3], -1, 0
	v_writelane_b32 v254, s2, 36
	s_cmp_eq_u32 s13, 9
	s_nop 0
	v_writelane_b32 v254, s3, 37
	s_cselect_b64 s[2:3], -1, 0
	v_writelane_b32 v254, s2, 38
	s_cmp_eq_u32 s13, 8
	s_nop 0
	v_writelane_b32 v254, s3, 39
	s_cselect_b64 s[2:3], -1, 0
	v_writelane_b32 v254, s2, 40
	s_cmp_eq_u32 s13, 7
	s_nop 0
	v_writelane_b32 v254, s3, 41
	s_cselect_b64 s[2:3], -1, 0
	v_writelane_b32 v254, s2, 42
	s_cmp_eq_u32 s13, 6
	s_nop 0
	v_writelane_b32 v254, s3, 43
	s_cselect_b64 s[2:3], -1, 0
	v_writelane_b32 v254, s2, 44
	s_cmp_eq_u32 s13, 5
	s_nop 0
	v_writelane_b32 v254, s3, 45
	s_cselect_b64 s[2:3], -1, 0
	v_writelane_b32 v254, s2, 46
	s_cmp_eq_u32 s13, 4
	s_nop 0
	v_writelane_b32 v254, s3, 47
	s_cselect_b64 s[2:3], -1, 0
	v_writelane_b32 v254, s2, 48
	s_cmp_eq_u32 s13, 3
	s_nop 0
	v_writelane_b32 v254, s3, 49
	s_cselect_b64 s[2:3], -1, 0
	v_writelane_b32 v254, s2, 50
	s_cmp_eq_u32 s13, 2
	s_nop 0
	v_writelane_b32 v254, s3, 51
	s_cselect_b64 s[2:3], -1, 0
	v_writelane_b32 v254, s2, 52
	s_cmp_eq_u32 s13, 1
	s_nop 0
	v_writelane_b32 v254, s3, 53
	s_cselect_b64 s[2:3], -1, 0
	v_writelane_b32 v254, s2, 54
	s_cmp_eq_u32 s13, 0
	s_nop 0
	v_writelane_b32 v254, s3, 55
	s_cselect_b64 s[2:3], -1, 0
	v_writelane_b32 v254, s2, 56
	s_lshl_b32 s4, s13, 8
	s_nop 0
	v_writelane_b32 v254, s3, 57
	s_add_u32 s2, s16, s4
	s_addc_u32 s3, s17, 0
	s_add_u32 s4, s2, 0x1400
	s_addc_u32 s5, s3, 0
	v_writelane_b32 v254, s4, 58
	s_add_u32 s2, s2, 0x2400
	s_addc_u32 s3, s3, 0
	v_writelane_b32 v254, s5, 59
	v_writelane_b32 v254, s2, 60
	s_mov_b32 s16, 0x6ca4000
	s_movk_i32 s17, 0x101
	v_writelane_b32 v254, s3, 61
	s_add_u32 s2, s58, 0x1de27400
	s_addc_u32 s3, s59, 0
	v_writelane_b32 v254, s2, 62
	s_nop 1
	v_writelane_b32 v254, s3, 63
	s_add_u32 s2, s58, 0x1de27500
	s_addc_u32 s3, s59, 0
	v_writelane_b32 v255, s2, 0
	s_nop 1
	v_writelane_b32 v255, s3, 1
	s_lshl_b32 s2, s10, 6
	s_and_b32 s2, s2, 0x80
	s_add_u32 s2, s18, s2
	v_writelane_b32 v255, s2, 2
	v_writelane_b32 v255, s18, 3
	s_addc_u32 s2, s19, 0
	s_ashr_i32 s11, s10, 31
	v_writelane_b32 v255, s19, 4
	v_writelane_b32 v255, s2, 5
	s_lshl_b64 s[2:3], s[10:11], 17
	s_add_u32 s4, s56, s2
	s_addc_u32 s5, s57, s3
	v_writelane_b32 v255, s4, 6
	s_lshl_b64 s[6:7], s[10:11], 16
	s_movk_i32 s11, 0x2000
	v_writelane_b32 v255, s5, 7
	s_ashr_i32 s5, s20, 31
	s_mov_b32 s4, s20
	s_lshl_b64 s[78:79], s[4:5], 17
	s_add_u32 s6, s58, s6
	s_addc_u32 s7, s59, s7
	s_add_u32 s6, s6, 0x2ca4000
	s_addc_u32 s7, s7, 0
	s_lshl_b64 s[96:97], s[4:5], 16
	v_writelane_b32 v255, s6, 8
	s_add_u32 s2, s60, s2
	s_addc_u32 s3, s61, s3
	v_writelane_b32 v255, s7, 9
	v_writelane_b32 v255, s2, 10
	s_mov_b32 s19, 0x41000000
	s_mov_b32 s18, 0x6d3c000
	v_writelane_b32 v255, s3, 11
	v_writelane_b32 v255, s1, 12
	s_lshl_b32 s1, s10, 5
	v_writelane_b32 v255, s1, 13
	s_lshl_b32 s1, s20, 5
	v_writelane_b32 v255, s1, 14
	s_lshl_b64 s[2:3], s[20:21], 11
	s_and_b32 s1, s0, 0x80
	v_writelane_b32 v255, s2, 15
	s_add_u32 s1, s58, s1
	s_mov_b32 s21, 0x6f04000
	v_writelane_b32 v255, s3, 16
	v_writelane_b32 v255, s1, 17
	s_addc_u32 s1, s59, 0
	v_writelane_b32 v255, s1, 18
	s_or_b32 s1, s8, 0x1b4d4000
	s_add_u32 s2, s58, 0x6ca6220
	v_writelane_b32 v255, s1, 19
	s_addc_u32 s3, s59, 0
	v_writelane_b32 v255, s2, 20
	s_lshl_b32 s0, s0, 1
	s_mov_b64 s[4:5], 0x5000
	v_writelane_b32 v255, s3, 21
	v_writelane_b32 v255, s0, 22
	s_mov_b32 s0, s10
	v_writelane_b32 v255, s0, 23
	s_mov_b32 s3, 0x800000
	s_movk_i32 s2, 0x4000
	v_writelane_b32 v255, s1, 24
	s_lshl_b32 s0, s10, 7
	v_writelane_b32 v255, s0, 25
	s_mov_b32 s0, s20
	v_writelane_b32 v255, s0, 26
	s_mov_b32 s10, 0x409b43d5
	s_nop 0
	v_writelane_b32 v255, s1, 27
	s_lshl_b32 s0, s20, 7
	v_writelane_b32 v255, s0, 28
	s_lshl_b32 s0, s9, 1
	v_writelane_b32 v255, s0, 29
	s_lshl_b32 s0, s14, 1
	v_writelane_b32 v255, s0, 30
	v_writelane_b32 v255, s9, 31
	s_lshl_b32 s0, s9, 5
	v_writelane_b32 v255, s0, 32
	v_writelane_b32 v255, s14, 33
	s_lshl_b32 s0, s14, 5
	v_writelane_b32 v255, s0, 34
	s_mov_b32 s1, 0x3fb55555
	v_writelane_b32 v255, s0, 35
	s_movk_i32 s20, 0x81
	s_mov_b32 s14, 0x3a800000
	v_writelane_b32 v255, s1, 36
	s_mov_b32 s1, 0x3f711111
	v_writelane_b32 v255, s0, 37
	s_mov_b64 s[8:9], 0x400
	s_nop 0
	v_writelane_b32 v255, s1, 38
	s_mov_b32 s1, 0x3f638138
	v_writelane_b32 v255, s0, 39
	s_nop 1
	v_writelane_b32 v255, s1, 40
	v_writelane_b32 v255, s30, 41
	s_nop 1
	v_writelane_b32 v255, s31, 42
	v_writelane_b32 v255, s96, 43
	s_nop 1
	v_writelane_b32 v255, s97, 44
	s_mov_b32 s0, 3
	s_nop 0
	v_writelane_b32 v255, s0, 62
	s_branch .LBB0_22

; DI void run_phase(const Params& p, int ph, char* smem, bool never) {
;     ...
;     else if (s == 1) { for (int i = B; i < 2048; i += G) mla_item(p, l, i, smem); }
;     else if (s == 2) {
;     ...
;       for (int w = lb; w < 256; w += nl) dense_item(p, l, xcd + 8 * (w >> 6), w & 63, smem, never);
;     ...
;       for (int i = B; i < 4096; i += G) band_item(p, l, i, smem);
;       for (int w = lb; w < 256; w += nl) { const int k = w >> 6, ck = ((k & 1) << 1 | (k >> 1)) ^ 1; dense_item(p, l, xcd + 8 * ck, w & 63, smem, true); }
;     }
.LBB0_57:
	s_and_b64 vcc, exec, s[0:1]
	s_cbranch_vccz .LBB0_203
	s_mov_b32 s0, 0
	s_nop 0
	v_writelane_b32 v255, s0, 62
.Lswap_band_entry:
	v_readlane_b32 s0, v255, 31
	v_readlane_b32 s1, v255, 62
	s_lshr_b32 s0, s0, 5
	s_and_b32 s0, s0, 1
	s_cmp_eq_u32 s1, 0
	s_cselect_b32 s1, 1, 0
	s_and_b32 s0, s0, s1
	s_cmp_eq_u32 s0, 1
	s_cbranch_scc0 .Lswap_band_go
	s_mov_b32 s0, 1
	s_nop 0
	v_writelane_b32 v255, s0, 62
	s_branch .LBB0_160
.Lswap_band_go:
	v_readlane_b32 s0, v253, 33
	v_readlane_b32 s1, v253, 34
	v_readlane_b32 s28, v255, 3
	s_andn2_b64 vcc, exec, s[0:1]
	v_readlane_b32 s29, v255, 4
	s_cbranch_vccnz .LBB0_160
	s_and_b64 s[0:1], s[86:87], exec
	v_readlane_b32 s0, v255, 23
	s_cselect_b32 s5, 0, 4
	s_mov_b32 s11, s0
	v_readlane_b32 s12, v255, 13
	s_mov_b32 s13, s0
	v_readlane_b32 s1, v255, 24
	s_branch .LBB0_62

; DI void run_phase(const Params& p, int ph, char* smem, bool never) {
;     ...
;       for (int i = B; i < 4096; i += G) band_item(p, l, i, smem);
;       for (int w = lb; w < 256; w += nl) { const int k = w >> 6, ck = ((k & 1) << 1 | (k >> 1)) ^ 1; dense_item(p, l, xcd + 8 * ck, w & 63, smem, true); }
.LBB0_160:
	v_readlane_b32 s0, v255, 31
	v_readlane_b32 s1, v255, 62
	s_lshr_b32 s0, s0, 5
	s_and_b32 s0, s0, 1
	s_cmp_eq_u32 s1, 2
	s_cselect_b32 s1, 1, 0
	s_and_b32 s0, s0, s1
	s_cmp_eq_u32 s0, 1
	s_cbranch_scc0 .Lswap_dense_go
	s_mov_b32 s0, 3
	s_nop 0
	v_writelane_b32 v255, s0, 62
	s_movk_i32 s11, 0x2000
	s_branch .LBB0_203

; DI void run_phase(const Params& p, int ph, char* smem, bool never) {
;     ...
;       for (int w = lb; w < 256; w += nl) { const int k = w >> 6, ck = ((k & 1) << 1 | (k >> 1)) ^ 1; dense_item(p, l, xcd + 8 * ck, w & 63, smem, true); }
;     }
.LBB0_203:
	v_readlane_b32 s0, v255, 31
	v_readlane_b32 s1, v255, 62
	s_lshr_b32 s0, s0, 5
	s_and_b32 s0, s0, 1
	s_cmp_eq_u32 s1, 1
	s_cselect_b32 s1, 1, 0
	s_and_b32 s0, s0, s1
	s_cmp_eq_u32 s0, 1
	s_cbranch_scc0 .Lswap_end_go
	s_mov_b32 s0, 2
	s_nop 0
	v_writelane_b32 v255, s0, 62
	s_branch .Lswap_band_entry
